# GEMM K-loops: all 16 LDS-DMA loads per iteration in SGPR-base form (no VALU address arithmetic left in the loops; the +0x80 bases kept in two spare SGPR pairs)
# baseline (speedup 1.0000x reference)
; #define PG8_STAGE(bufoff, gbase, voff) do { _Pragma("unroll") for (int _i = 0; _i < 2; ++_i) \
;         __builtin_amdgcn_global_load_lds((const unsigned*)((const char*)(gbase) + (voff)[_i]), (LAS unsigned*)(lds + (bufoff) + ldsw + _i * 8192), 16, 0, 0); } while (0)
; #define PG8_LDA(dst, b, h) do { _Pragma("unroll") for (int m = 0; m < 4; ++m) _Pragma("unroll") for (int k = 0; k < 2; ++k) dst[m][k] = *(const LAS bf16x8*)(lds + PG8_SA(b, h) + aoff + m * 2048 + k * 1024); } while (0)
; #define PG8_LDB(dst, b, h) do { _Pragma("unroll") for (int n = 0; n < 2; ++n) _Pragma("unroll") for (int k = 0; k < 2; ++k) dst[n][k] = *(const LAS bf16x8*)(lds + PG8_SB(b, h) + boff + n * 2048 + k * 1024); } while (0)
; #define PG8_MMA(ai, bj, At, Bt) do { __builtin_amdgcn_s_setprio(1); _Pragma("unroll") for (int m = 0; m < 4; ++m) _Pragma("unroll") for (int n = 0; n < 2; ++n) _Pragma("unroll") for (int k = 0; k < 2; ++k) \
;         acc[ai][bj][m][n] = __builtin_amdgcn_mfma_f32_16x16x32_bf16(Bt[n][k], At[m][k], acc[ai][bj][m][n], 0, 0, 0); __builtin_amdgcn_s_setprio(0); } while (0)
; #define PG8_WAIT_V(n) asm volatile("s_waitcnt vmcnt(" #n ")" ::: "memory")
; #define PG8_WAIT_L(n) asm volatile("s_waitcnt lgkmcnt(" #n ")" ::: "memory")
; #define PG8_BAR __builtin_amdgcn_s_barrier()
; #define PG8_SCHED __builtin_amdgcn_sched_barrier(0)
; template <class Epi>
; __device__ __forceinline__ void gemm_phase(LAS unsigned char* lds, const Gemm g, const StaticOrder& S, const Epi& E) {
;     ...
;             PG8_LDB(B0, 0, 0); PG8_SCHED; PG8_LDA(At, 0, 0); PG8_STAGE(PG8_SA(1, 1), a1 + hstep, voffA);
;             PG8_WAIT_L(8); PG8_BAR; PG8_WAIT_L(0); PG8_MMA(0, 0, At, B0); PG8_BAR; PG8_SCHED;
;             PG8_LDB(B1, 0, 1); PG8_STAGE(PG8_SB(0, 0), b2, voffB);
;             PG8_BAR; PG8_WAIT_L(0); PG8_MMA(0, 1, At, B1); PG8_BAR;
;             PG8_LDA(At, 0, 1); PG8_STAGE(PG8_SA(0, 0), a2, voffA);
;             PG8_BAR; PG8_WAIT_L(0); PG8_MMA(1, 0, At, B0); PG8_BAR; PG8_SCHED;
;             PG8_STAGE(PG8_SB(0, 1), b2 + hstep, voffB);
;             PG8_WAIT_V(6); PG8_BAR; PG8_MMA(1, 1, At, B1); PG8_BAR;
.LBB0_80:
	ds_read_b128 v[154:157], v173
	ds_read_b128 v[176:179], v173 offset:1024
	ds_read_b128 v[180:183], v173 offset:2048
	ds_read_b128 v[184:187], v173 offset:3072
	s_add_u32 s26, s12, 0xfff80080
	s_addc_u32 s27, s13, -1
	s_cmp_eq_u32 s67, 28
	s_cselect_b32 s29, s7, s27
	s_cselect_b32 s28, s63, s26
	s_cselect_b32 s27, s25, s66
	s_cselect_b32 s26, s64, s65
	s_add_i32 m0, s42, 0xc000
	ds_read_b128 v[188:191], v174
	ds_read_b128 v[192:195], v174 offset:1024
	ds_read_b128 v[196:199], v174 offset:2048
	ds_read_b128 v[200:203], v174 offset:3072
	ds_read_b128 v[204:207], v174 offset:4096
	ds_read_b128 v[208:211], v174 offset:5120
	ds_read_b128 v[212:215], v174 offset:6144
	ds_read_b128 v[216:219], v174 offset:7168
	global_load_lds_dwordx4 v146, s[12:13]
	s_add_i32 m0, s42, 0xe000
	s_nop 0
	global_load_lds_dwordx4 v148, s[12:13]
	s_waitcnt lgkmcnt(8)
	s_barrier
	s_waitcnt lgkmcnt(0)
	s_waitcnt lgkmcnt(0)
	v_mfma_f32_16x16x32_bf16 v[124:127], v[154:157], v[188:191], v[124:127]
	v_mfma_f32_16x16x32_bf16 v[120:123], v[180:183], v[188:191], v[120:123]
	v_mfma_f32_16x16x32_bf16 v[116:119], v[154:157], v[196:199], v[116:119]
	v_mfma_f32_16x16x32_bf16 v[112:115], v[180:183], v[196:199], v[112:115]
	v_mfma_f32_16x16x32_bf16 v[100:103], v[154:157], v[204:207], v[100:103]
	v_mfma_f32_16x16x32_bf16 v[96:99], v[180:183], v[204:207], v[96:99]
	v_mfma_f32_16x16x32_bf16 v[76:79], v[154:157], v[212:215], v[76:79]
	v_mfma_f32_16x16x32_bf16 v[72:75], v[180:183], v[212:215], v[72:75]
	v_mfma_f32_16x16x32_bf16 v[124:127], v[176:179], v[192:195], v[124:127]
	v_mfma_f32_16x16x32_bf16 v[120:123], v[184:187], v[192:195], v[120:123]
	v_mfma_f32_16x16x32_bf16 v[116:119], v[176:179], v[200:203], v[116:119]
	v_mfma_f32_16x16x32_bf16 v[112:115], v[184:187], v[200:203], v[112:115]
	v_mfma_f32_16x16x32_bf16 v[100:103], v[176:179], v[208:211], v[100:103]
	v_mfma_f32_16x16x32_bf16 v[96:99], v[184:187], v[208:211], v[96:99]
	v_mfma_f32_16x16x32_bf16 v[76:79], v[176:179], v[216:219], v[76:79]
	v_mfma_f32_16x16x32_bf16 v[72:75], v[184:187], v[216:219], v[72:75]
	s_barrier
	s_add_i32 s68, s55, s35
	s_add_u32 s72, s26, 0x80
	s_addc_u32 s73, s27, 0
	s_mov_b32 m0, s68
	ds_read_b128 v[220:223], v175
	ds_read_b128 v[224:227], v175 offset:1024
	ds_read_b128 v[228:231], v175 offset:2048
	ds_read_b128 v[232:235], v175 offset:3072
	global_load_lds_dwordx4 v140, s[26:27]
	s_add_i32 m0, s68, 0x2000
	s_nop 0
	global_load_lds_dwordx4 v136, s[26:27]
	s_barrier
	s_waitcnt lgkmcnt(0)
	s_waitcnt lgkmcnt(0)
	v_mfma_f32_16x16x32_bf16 v[108:111], v[220:223], v[188:191], v[108:111]
	v_mfma_f32_16x16x32_bf16 v[104:107], v[228:231], v[188:191], v[104:107]
	v_mfma_f32_16x16x32_bf16 v[92:95], v[220:223], v[196:199], v[92:95]
	v_mfma_f32_16x16x32_bf16 v[88:91], v[228:231], v[196:199], v[88:91]
	v_mfma_f32_16x16x32_bf16 v[84:87], v[220:223], v[204:207], v[84:87]
	v_mfma_f32_16x16x32_bf16 v[80:83], v[228:231], v[204:207], v[80:83]
	v_mfma_f32_16x16x32_bf16 v[68:71], v[220:223], v[212:215], v[68:71]
	v_mfma_f32_16x16x32_bf16 v[64:67], v[228:231], v[212:215], v[64:67]
	v_mfma_f32_16x16x32_bf16 v[108:111], v[224:227], v[192:195], v[108:111]
	v_mfma_f32_16x16x32_bf16 v[104:107], v[232:235], v[192:195], v[104:107]
	v_mfma_f32_16x16x32_bf16 v[92:95], v[224:227], v[200:203], v[92:95]
	v_mfma_f32_16x16x32_bf16 v[88:91], v[232:235], v[200:203], v[88:91]
	v_mfma_f32_16x16x32_bf16 v[84:87], v[224:227], v[208:211], v[84:87]
	v_mfma_f32_16x16x32_bf16 v[80:83], v[232:235], v[208:211], v[80:83]
	v_mfma_f32_16x16x32_bf16 v[68:71], v[224:227], v[216:219], v[68:71]
	v_mfma_f32_16x16x32_bf16 v[64:67], v[232:235], v[216:219], v[64:67]
	s_mov_b32 m0, s42
	s_add_u32 s74, s28, 0x80
	s_addc_u32 s75, s29, 0
	s_barrier
	ds_read_b128 v[188:191], v174 offset:16384
	ds_read_b128 v[192:195], v174 offset:17408
	ds_read_b128 v[196:199], v174 offset:18432
	ds_read_b128 v[200:203], v174 offset:19456
	ds_read_b128 v[204:207], v174 offset:20480
	ds_read_b128 v[208:211], v174 offset:21504
	ds_read_b128 v[212:215], v174 offset:22528
	ds_read_b128 v[216:219], v174 offset:23552
	global_load_lds_dwordx4 v142, s[28:29]
	s_mov_b32 m0, s43
	s_nop 0
	global_load_lds_dwordx4 v138, s[28:29]
	s_barrier
	s_waitcnt lgkmcnt(0)
	s_waitcnt lgkmcnt(0)
	v_mfma_f32_16x16x32_bf16 v[60:63], v[154:157], v[188:191], v[60:63]
	v_mfma_f32_16x16x32_bf16 v[56:59], v[180:183], v[188:191], v[56:59]
	v_mfma_f32_16x16x32_bf16 v[52:55], v[154:157], v[196:199], v[52:55]
	v_mfma_f32_16x16x32_bf16 v[48:51], v[180:183], v[196:199], v[48:51]
	v_mfma_f32_16x16x32_bf16 v[36:39], v[154:157], v[204:207], v[36:39]
	v_mfma_f32_16x16x32_bf16 v[32:35], v[180:183], v[204:207], v[32:35]
	v_mfma_f32_16x16x32_bf16 v[12:15], v[154:157], v[212:215], v[12:15]
	v_mfma_f32_16x16x32_bf16 v[8:11], v[180:183], v[212:215], v[8:11]
	v_mfma_f32_16x16x32_bf16 v[60:63], v[176:179], v[192:195], v[60:63]
	v_mfma_f32_16x16x32_bf16 v[56:59], v[184:187], v[192:195], v[56:59]
	v_mfma_f32_16x16x32_bf16 v[52:55], v[176:179], v[200:203], v[52:55]
	v_mfma_f32_16x16x32_bf16 v[48:51], v[184:187], v[200:203], v[48:51]
	v_mfma_f32_16x16x32_bf16 v[36:39], v[176:179], v[208:211], v[36:39]
	v_mfma_f32_16x16x32_bf16 v[32:35], v[184:187], v[208:211], v[32:35]
	v_mfma_f32_16x16x32_bf16 v[12:15], v[176:179], v[216:219], v[12:15]
	v_mfma_f32_16x16x32_bf16 v[8:11], v[184:187], v[216:219], v[8:11]
	s_barrier
	s_add_u32 s68, s26, 0x80000
	s_addc_u32 s69, s27, 0
	s_add_i32 s70, s56, s35
	s_mov_b32 m0, s70
	s_nop 0
	global_load_lds_dwordx4 v140, s[68:69]
	s_add_i32 m0, s70, 0x2000
	s_nop 0
	global_load_lds_dwordx4 v136, s[68:69]
	s_waitcnt vmcnt(6)
	s_barrier
; #define PG8_STAGE(bufoff, gbase, voff) do { _Pragma("unroll") for (int _i = 0; _i < 2; ++_i) \
;         __builtin_amdgcn_global_load_lds((const unsigned*)((const char*)(gbase) + (voff)[_i]), (LAS unsigned*)(lds + (bufoff) + ldsw + _i * 8192), 16, 0, 0); } while (0)
; #define PG8_LDA(dst, b, h) do { _Pragma("unroll") for (int m = 0; m < 4; ++m) _Pragma("unroll") for (int k = 0; k < 2; ++k) dst[m][k] = *(const LAS bf16x8*)(lds + PG8_SA(b, h) + aoff + m * 2048 + k * 1024); } while (0)
; #define PG8_LDB(dst, b, h) do { _Pragma("unroll") for (int n = 0; n < 2; ++n) _Pragma("unroll") for (int k = 0; k < 2; ++k) dst[n][k] = *(const LAS bf16x8*)(lds + PG8_SB(b, h) + boff + n * 2048 + k * 1024); } while (0)
; #define PG8_MMA(ai, bj, At, Bt) do { __builtin_amdgcn_s_setprio(1); _Pragma("unroll") for (int m = 0; m < 4; ++m) _Pragma("unroll") for (int n = 0; n < 2; ++n) _Pragma("unroll") for (int k = 0; k < 2; ++k) \
;         acc[ai][bj][m][n] = __builtin_amdgcn_mfma_f32_16x16x32_bf16(Bt[n][k], At[m][k], acc[ai][bj][m][n], 0, 0, 0); __builtin_amdgcn_s_setprio(0); } while (0)
; #define PG8_WAIT_V(n) asm volatile("s_waitcnt vmcnt(" #n ")" ::: "memory")
; #define PG8_WAIT_L(n) asm volatile("s_waitcnt lgkmcnt(" #n ")" ::: "memory")
; #define PG8_BAR __builtin_amdgcn_s_barrier()
; #define PG8_SCHED __builtin_amdgcn_sched_barrier(0)
; template <class Epi>
; __device__ __forceinline__ void gemm_phase(LAS unsigned char* lds, const Gemm g, const StaticOrder& S, const Epi& E) {
;     ...
;             PG8_WAIT_V(6); PG8_BAR; PG8_MMA(1, 1, At, B1); PG8_BAR;
;             PG8_LDB(B0, 1, 0); PG8_SCHED; PG8_LDA(At, 1, 0); PG8_STAGE(PG8_SA(0, 1), a2 + hstep, voffA);
;             PG8_WAIT_L(8); PG8_BAR; PG8_WAIT_L(0); PG8_MMA(0, 0, At, B0); PG8_BAR; PG8_SCHED;
;             PG8_LDB(B1, 1, 1); PG8_STAGE(PG8_SB(1, 0), b3, voffB);
;             PG8_BAR; PG8_WAIT_L(0); PG8_MMA(0, 1, At, B1); PG8_BAR;
;             PG8_LDA(At, 1, 1); PG8_STAGE(PG8_SA(1, 0), a3, voffA);
	v_mfma_f32_16x16x32_bf16 v[44:47], v[220:223], v[188:191], v[44:47]
	v_mfma_f32_16x16x32_bf16 v[40:43], v[228:231], v[188:191], v[40:43]
	v_mfma_f32_16x16x32_bf16 v[28:31], v[220:223], v[196:199], v[28:31]
	v_mfma_f32_16x16x32_bf16 v[24:27], v[228:231], v[196:199], v[24:27]
	v_mfma_f32_16x16x32_bf16 v[20:23], v[220:223], v[204:207], v[20:23]
	v_mfma_f32_16x16x32_bf16 v[16:19], v[228:231], v[204:207], v[16:19]
	v_mfma_f32_16x16x32_bf16 v[4:7], v[220:223], v[212:215], v[4:7]
	v_mfma_f32_16x16x32_bf16 v[0:3], v[228:231], v[212:215], v[0:3]
	v_mfma_f32_16x16x32_bf16 v[44:47], v[224:227], v[192:195], v[44:47]
	v_mfma_f32_16x16x32_bf16 v[40:43], v[232:235], v[192:195], v[40:43]
	v_mfma_f32_16x16x32_bf16 v[28:31], v[224:227], v[200:203], v[28:31]
	v_mfma_f32_16x16x32_bf16 v[24:27], v[232:235], v[200:203], v[24:27]
	v_mfma_f32_16x16x32_bf16 v[20:23], v[224:227], v[208:211], v[20:23]
	v_mfma_f32_16x16x32_bf16 v[16:19], v[232:235], v[208:211], v[16:19]
	v_mfma_f32_16x16x32_bf16 v[4:7], v[224:227], v[216:219], v[4:7]
	v_mfma_f32_16x16x32_bf16 v[0:3], v[232:235], v[216:219], v[0:3]
	s_add_i32 s68, 0, 0x18000
	v_add_u32_e32 v144, s68, v135
	s_barrier
	ds_read_b128 v[154:157], v144
	ds_read_b128 v[176:179], v144 offset:1024
	ds_read_b128 v[180:183], v144 offset:2048
	ds_read_b128 v[184:187], v144 offset:3072
	s_add_u32 s28, s28, 0x80000
	s_addc_u32 s29, s29, 0
	s_mov_b32 m0, s44
	ds_read_b128 v[188:191], v174 offset:32768
	ds_read_b128 v[192:195], v174 offset:33792
	ds_read_b128 v[196:199], v174 offset:34816
	ds_read_b128 v[200:203], v174 offset:35840
	ds_read_b128 v[204:207], v174 offset:36864
	ds_read_b128 v[208:211], v174 offset:37888
	ds_read_b128 v[212:215], v174 offset:38912
	ds_read_b128 v[216:219], v174 offset:39936
	global_load_lds_dwordx4 v142, s[28:29]
	s_mov_b32 m0, s45
	s_nop 0
	global_load_lds_dwordx4 v138, s[28:29]
	s_waitcnt lgkmcnt(8)
	s_barrier
	s_waitcnt lgkmcnt(0)
	s_waitcnt lgkmcnt(0)
	v_mfma_f32_16x16x32_bf16 v[124:127], v[154:157], v[188:191], v[124:127]
	v_mfma_f32_16x16x32_bf16 v[120:123], v[180:183], v[188:191], v[120:123]
	v_mfma_f32_16x16x32_bf16 v[116:119], v[154:157], v[196:199], v[116:119]
	v_mfma_f32_16x16x32_bf16 v[112:115], v[180:183], v[196:199], v[112:115]
	v_mfma_f32_16x16x32_bf16 v[100:103], v[154:157], v[204:207], v[100:103]
	v_mfma_f32_16x16x32_bf16 v[96:99], v[180:183], v[204:207], v[96:99]
	v_mfma_f32_16x16x32_bf16 v[76:79], v[154:157], v[212:215], v[76:79]
	v_mfma_f32_16x16x32_bf16 v[72:75], v[180:183], v[212:215], v[72:75]
	v_mfma_f32_16x16x32_bf16 v[124:127], v[176:179], v[192:195], v[124:127]
	v_mfma_f32_16x16x32_bf16 v[120:123], v[184:187], v[192:195], v[120:123]
	v_mfma_f32_16x16x32_bf16 v[116:119], v[176:179], v[200:203], v[116:119]
	v_mfma_f32_16x16x32_bf16 v[112:115], v[184:187], v[200:203], v[112:115]
	v_mfma_f32_16x16x32_bf16 v[100:103], v[176:179], v[208:211], v[100:103]
	v_mfma_f32_16x16x32_bf16 v[96:99], v[184:187], v[208:211], v[96:99]
	v_mfma_f32_16x16x32_bf16 v[76:79], v[176:179], v[216:219], v[76:79]
	v_mfma_f32_16x16x32_bf16 v[72:75], v[184:187], v[216:219], v[72:75]
	s_barrier
	s_add_i32 s28, 0, 0x1c000
	s_add_i32 s29, s68, s35
	v_add_u32_e32 v144, s28, v135
	s_mov_b32 m0, s29
	ds_read_b128 v[220:223], v144
	ds_read_b128 v[224:227], v144 offset:1024
	ds_read_b128 v[228:231], v144 offset:2048
	ds_read_b128 v[232:235], v144 offset:3072
	global_load_lds_dwordx4 v140, s[72:73]
	s_add_i32 m0, s29, 0x2000
	s_nop 0
	global_load_lds_dwordx4 v136, s[72:73]
	s_barrier
	s_waitcnt lgkmcnt(0)
	s_waitcnt lgkmcnt(0)
	v_mfma_f32_16x16x32_bf16 v[108:111], v[220:223], v[188:191], v[108:111]
	v_mfma_f32_16x16x32_bf16 v[104:107], v[228:231], v[188:191], v[104:107]
	v_mfma_f32_16x16x32_bf16 v[92:95], v[220:223], v[196:199], v[92:95]
	v_mfma_f32_16x16x32_bf16 v[88:91], v[228:231], v[196:199], v[88:91]
	v_mfma_f32_16x16x32_bf16 v[84:87], v[220:223], v[204:207], v[84:87]
	v_mfma_f32_16x16x32_bf16 v[80:83], v[228:231], v[204:207], v[80:83]
	v_mfma_f32_16x16x32_bf16 v[68:71], v[220:223], v[212:215], v[68:71]
	v_mfma_f32_16x16x32_bf16 v[64:67], v[228:231], v[212:215], v[64:67]
	v_mfma_f32_16x16x32_bf16 v[108:111], v[224:227], v[192:195], v[108:111]
	v_mfma_f32_16x16x32_bf16 v[104:107], v[232:235], v[192:195], v[104:107]
	v_mfma_f32_16x16x32_bf16 v[92:95], v[224:227], v[200:203], v[92:95]
	v_mfma_f32_16x16x32_bf16 v[88:91], v[232:235], v[200:203], v[88:91]
	v_mfma_f32_16x16x32_bf16 v[84:87], v[224:227], v[208:211], v[84:87]
	v_mfma_f32_16x16x32_bf16 v[80:83], v[232:235], v[208:211], v[80:83]
	v_mfma_f32_16x16x32_bf16 v[68:71], v[224:227], v[216:219], v[68:71]
	v_mfma_f32_16x16x32_bf16 v[64:67], v[232:235], v[216:219], v[64:67]
	s_mov_b32 m0, s48
	s_barrier
	ds_read_b128 v[188:191], v174 offset:49152
	ds_read_b128 v[192:195], v174 offset:50176
	ds_read_b128 v[196:199], v174 offset:51200
	ds_read_b128 v[200:203], v174 offset:52224
	ds_read_b128 v[204:207], v174 offset:53248
	ds_read_b128 v[208:211], v174 offset:54272
	ds_read_b128 v[212:215], v174 offset:55296
	ds_read_b128 v[216:219], v174 offset:56320
	global_load_lds_dwordx4 v142, s[74:75]
	s_mov_b32 m0, s49
	s_nop 0
	global_load_lds_dwordx4 v138, s[74:75]
	s_barrier
; __device__ __forceinline__ unsigned pk_bf16(float lo, float hi) { const f32x2 v = (f32x2){lo, hi}; const bf16v2 b = __builtin_convertvector(v, bf16v2); return __builtin_bit_cast(unsigned, b); }
; #define PG8_STAGE(bufoff, gbase, voff) do { _Pragma("unroll") for (int _i = 0; _i < 2; ++_i) \
;         __builtin_amdgcn_global_load_lds((const unsigned*)((const char*)(gbase) + (voff)[_i]), (LAS unsigned*)(lds + (bufoff) + ldsw + _i * 8192), 16, 0, 0); } while (0)
; #define PG8_BAR __builtin_amdgcn_s_barrier()
; template <class Epi>
; __device__ __forceinline__ void gemm_phase(LAS unsigned char* lds, const Gemm g, const StaticOrder& S, const Epi& E) {
;     ...
;             PG8_BAR; PG8_WAIT_L(0); PG8_MMA(0, 1, At, B1); PG8_BAR;
;             PG8_LDA(At, 1, 1); PG8_STAGE(PG8_SA(1, 0), a3, voffA);
;             PG8_BAR; PG8_WAIT_L(0); PG8_MMA(1, 0, At, B0); PG8_BAR; PG8_SCHED;
;             PG8_STAGE(PG8_SB(1, 1), b3 + hstep, voffB);
;             PG8_WAIT_V(6); PG8_BAR; PG8_MMA(1, 1, At, B1); PG8_BAR;
;     __device__ __forceinline__ void operator()(const f32x4 (&acc)[2][2][4][2], const pg8::Unit& u, int wr, int wc, int fr, int fq) const {
;         const int row0 = u.pm * 256 + wr * 64 + fr, col0 = u.pn * 256 + wc * 32 + 8 * fq;
; #pragma unroll
;         for (int ai = 0; ai < 2; ++ai)
; #pragma unroll
;             for (int m = 0; m < 4; ++m) {
;                 const int row = row0 + ai * 128 + m * 16;
;                 bf16_t* rowp = Z + (size_t)row * LDZ + col0;
;                 const bool last = ((row & 63) == 63) && (row >= MP || (row & (SEQ - 1)) == SEQ - 1);
; #pragma unroll
;                 for (int bj = 0; bj < 2; ++bj) {
;                     const f32x4 v0 = acc[ai][bj][m][0], v1 = acc[ai][bj][m][1];
;                     u32x4 w; w.x = pk_bf16(v0[0], v0[1]); w.y = pk_bf16(v0[2], v0[3]); w.z = pk_bf16(v1[0], v1[1]); w.w = pk_bf16(v1[2], v1[3]);
;                     *(u32x4*)(rowp + bj * 128) = w;
;                     if (last) {
;                         const int c = col0 + bj * 128 - ZC_S;
;                         if (c >= 0 && c < NSHIFT) {
;                             float* o = row < MP ? out + O_SHP + (size_t)(row >> 13) * NSHIFT + c : out + O_SHS + (size_t)((row - MP) >> 6) * NSHIFT + c;
;                             *(f32x4*)o = v0; *(f32x4*)(o + 4) = v1;
;                         }
;                     }
;                 }
	s_waitcnt lgkmcnt(0)
	s_waitcnt lgkmcnt(0)
	v_mfma_f32_16x16x32_bf16 v[60:63], v[154:157], v[188:191], v[60:63]
	v_mfma_f32_16x16x32_bf16 v[56:59], v[180:183], v[188:191], v[56:59]
	v_mfma_f32_16x16x32_bf16 v[52:55], v[154:157], v[196:199], v[52:55]
	v_mfma_f32_16x16x32_bf16 v[48:51], v[180:183], v[196:199], v[48:51]
	v_mfma_f32_16x16x32_bf16 v[36:39], v[154:157], v[204:207], v[36:39]
	v_mfma_f32_16x16x32_bf16 v[32:35], v[180:183], v[204:207], v[32:35]
	v_mfma_f32_16x16x32_bf16 v[12:15], v[154:157], v[212:215], v[12:15]
	v_mfma_f32_16x16x32_bf16 v[8:11], v[180:183], v[212:215], v[8:11]
	v_mfma_f32_16x16x32_bf16 v[60:63], v[176:179], v[192:195], v[60:63]
	v_mfma_f32_16x16x32_bf16 v[56:59], v[184:187], v[192:195], v[56:59]
	v_mfma_f32_16x16x32_bf16 v[52:55], v[176:179], v[200:203], v[52:55]
	v_mfma_f32_16x16x32_bf16 v[48:51], v[184:187], v[200:203], v[48:51]
	v_mfma_f32_16x16x32_bf16 v[36:39], v[176:179], v[208:211], v[36:39]
	v_mfma_f32_16x16x32_bf16 v[32:35], v[184:187], v[208:211], v[32:35]
	v_mfma_f32_16x16x32_bf16 v[12:15], v[176:179], v[216:219], v[12:15]
	v_mfma_f32_16x16x32_bf16 v[8:11], v[184:187], v[216:219], v[8:11]
	s_barrier
	s_add_u32 s26, s26, 0x80080
	s_addc_u32 s27, s27, 0
	s_add_i32 s28, s28, s35
	s_mov_b32 m0, s28
	s_nop 0
	global_load_lds_dwordx4 v140, s[26:27]
	s_add_i32 m0, s28, 0x2000
	s_nop 0
	global_load_lds_dwordx4 v136, s[26:27]
	s_waitcnt vmcnt(6)
	s_barrier
	v_mfma_f32_16x16x32_bf16 v[44:47], v[220:223], v[188:191], v[44:47]
	v_mfma_f32_16x16x32_bf16 v[40:43], v[228:231], v[188:191], v[40:43]
	v_mfma_f32_16x16x32_bf16 v[28:31], v[220:223], v[196:199], v[28:31]
	v_mfma_f32_16x16x32_bf16 v[24:27], v[228:231], v[196:199], v[24:27]
	v_mfma_f32_16x16x32_bf16 v[20:23], v[220:223], v[204:207], v[20:23]
	v_mfma_f32_16x16x32_bf16 v[16:19], v[228:231], v[204:207], v[16:19]
	v_mfma_f32_16x16x32_bf16 v[4:7], v[220:223], v[212:215], v[4:7]
	v_mfma_f32_16x16x32_bf16 v[0:3], v[228:231], v[212:215], v[0:3]
	v_mfma_f32_16x16x32_bf16 v[44:47], v[224:227], v[192:195], v[44:47]
	v_mfma_f32_16x16x32_bf16 v[40:43], v[232:235], v[192:195], v[40:43]
	v_mfma_f32_16x16x32_bf16 v[28:31], v[224:227], v[200:203], v[28:31]
	v_mfma_f32_16x16x32_bf16 v[24:27], v[232:235], v[200:203], v[24:27]
	v_mfma_f32_16x16x32_bf16 v[20:23], v[224:227], v[208:211], v[20:23]
	v_mfma_f32_16x16x32_bf16 v[16:19], v[232:235], v[208:211], v[16:19]
	v_mfma_f32_16x16x32_bf16 v[4:7], v[224:227], v[216:219], v[4:7]
	v_mfma_f32_16x16x32_bf16 v[0:3], v[232:235], v[216:219], v[0:3]
	s_add_i32 s67, s67, 2
	s_add_u32 s12, s12, 0x100
	s_addc_u32 s13, s13, 0
	s_add_u32 s65, s65, 0x100
	s_addc_u32 s66, s66, 0
	s_cmp_gt_u32 s67, 29
	s_barrier
	s_cbranch_scc0 .LBB0_80
	s_lshl_b32 s7, s31, 8
	s_add_i32 s7, s7, s47
	v_lshl_or_b32 v156, s30, 8, v172
	s_add_i32 s12, s7, 0xffff8000
	v_or_b32_e32 v176, s7, v161
	v_ashrrev_i32_e32 v157, 31, v156
	s_lshr_b32 s63, s12, 6
	s_ashr_i32 s12, s7, 13
	v_mov_b64_e32 v[178:179], s[14:15]
	s_mul_i32 s26, s12, 0xc80
	v_mad_i64_i32 v[180:181], s[12:13], v176, s58, v[178:179]
	v_lshlrev_b64 v[154:155], 1, v[156:157]
	v_cvt_pk_bf16_f32 v108, v108, v109
	v_cvt_pk_bf16_f32 v109, v110, v111
	v_cvt_pk_bf16_f32 v110, v104, v105
	v_or_b32_e32 v104, 16, v176
	v_cvt_pk_bf16_f32 v92, v92, v93
	v_cvt_pk_bf16_f32 v93, v94, v95
	v_cvt_pk_bf16_f32 v94, v88, v89
	v_or_b32_e32 v88, 32, v176
	v_cvt_pk_bf16_f32 v84, v84, v85
	v_cvt_pk_bf16_f32 v85, v86, v87
	v_cvt_pk_bf16_f32 v87, v82, v83
	v_or_b32_e32 v82, 48, v176
	v_lshl_add_u64 v[180:181], v[180:181], 0, v[154:155]
	v_cvt_pk_bf16_f32 v111, v106, v107
	v_mad_i64_i32 v[104:105], s[12:13], v104, s58, v[178:179]
	v_mad_i64_i32 v[88:89], s[12:13], v88, s58, v[178:179]
	v_cvt_pk_bf16_f32 v86, v80, v81
	v_mad_i64_i32 v[80:81], s[12:13], v82, s58, v[178:179]
	v_bitop3_b32 v83, v176, s60, 48 bitop3:0xc8
	global_store_dwordx4 v[180:181], v[108:111], off offset:256
	v_cvt_pk_bf16_f32 v95, v90, v91
	v_cmp_lt_i32_e32 vcc, s59, v82
	v_lshl_add_u64 v[108:109], v[104:105], 0, v[154:155]
	v_cmp_eq_u32_e64 s[12:13], s60, v83
	global_store_dwordx4 v[108:109], v[92:95], off offset:256
	s_or_b64 s[12:13], vcc, s[12:13]
	s_mul_hi_u32 s25, s63, 0x3200
	v_lshl_add_u64 v[92:93], v[88:89], 0, v[154:155]
	s_mulk_i32 s63, 0x3200
	s_ashr_i32 s27, s26, 31
	v_cvt_pk_bf16_f32 v124, v124, v125
	v_cvt_pk_bf16_f32 v125, v126, v127
	v_cvt_pk_bf16_f32 v126, v120, v121
	v_cvt_pk_bf16_f32 v127, v122, v123
	v_cvt_pk_bf16_f32 v104, v116, v117
	v_cvt_pk_bf16_f32 v105, v118, v119
	v_cvt_pk_bf16_f32 v106, v112, v113
	v_cvt_pk_bf16_f32 v107, v114, v115
	v_cvt_pk_bf16_f32 v88, v100, v101
	v_cvt_pk_bf16_f32 v89, v102, v103
	v_cvt_pk_bf16_f32 v90, v96, v97
	v_cvt_pk_bf16_f32 v91, v98, v99
	global_store_dwordx4 v[92:93], v[84:87], off offset:256
	v_lshl_add_u64 v[80:81], v[80:81], 0, v[154:155]
	s_and_b64 s[28:29], s[8:9], s[12:13]
	v_cmp_gt_i32_e32 vcc, s50, v82
	v_cvt_pk_bf16_f32 v82, v76, v77
	v_cvt_pk_bf16_f32 v83, v78, v79
	v_cvt_pk_bf16_f32 v84, v72, v73
	v_cvt_pk_bf16_f32 v85, v74, v75
	v_add_u32_e32 v144, 0xfffff400, v156
	global_store_dwordx4 v[180:181], v[124:127], off
	global_store_dwordx4 v[108:109], v[104:107], off
	global_store_dwordx4 v[92:93], v[88:91], off
	global_store_dwordx4 v[80:81], v[82:85], off
	s_and_saveexec_b64 s[30:31], s[28:29]
	s_cbranch_execz .LBB0_84
	v_cmp_gt_u32_e64 s[12:13], s57, v144
	s_and_b64 exec, exec, s[12:13]
	s_cbranch_execz .LBB0_84
	s_lshl_b64 s[12:13], s[26:27], 2
	s_add_u32 s12, s22, s12
	s_addc_u32 s13, s23, s13
	s_add_u32 s64, s51, s63
	s_addc_u32 s65, s52, s25
	v_mov_b32_e32 v82, s65
	v_mov_b32_e32 v83, s13
	v_cndmask_b32_e32 v83, v82, v83, vcc
	v_mov_b32_e32 v82, s64
	v_mov_b32_e32 v84, s12
	v_cndmask_b32_e32 v82, v82, v84, vcc
	v_lshl_add_u64 v[82:83], v[144:145], 2, v[82:83]
	global_store_dwordx4 v[82:83], v[76:79], off
	global_store_dwordx4 v[82:83], v[72:75], off offset:16

; #define PG8_STAGE(bufoff, gbase, voff) do { _Pragma("unroll") for (int _i = 0; _i < 2; ++_i) \
;         __builtin_amdgcn_global_load_lds((const unsigned*)((const char*)(gbase) + (voff)[_i]), (LAS unsigned*)(lds + (bufoff) + ldsw + _i * 8192), 16, 0, 0); } while (0)
; #define PG8_LDA(dst, b, h) do { _Pragma("unroll") for (int m = 0; m < 4; ++m) _Pragma("unroll") for (int k = 0; k < 2; ++k) dst[m][k] = *(const LAS bf16x8*)(lds + PG8_SA(b, h) + aoff + m * 2048 + k * 1024); } while (0)
; #define PG8_LDB(dst, b, h) do { _Pragma("unroll") for (int n = 0; n < 2; ++n) _Pragma("unroll") for (int k = 0; k < 2; ++k) dst[n][k] = *(const LAS bf16x8*)(lds + PG8_SB(b, h) + boff + n * 2048 + k * 1024); } while (0)
; #define PG8_MMA(ai, bj, At, Bt) do { __builtin_amdgcn_s_setprio(1); _Pragma("unroll") for (int m = 0; m < 4; ++m) _Pragma("unroll") for (int n = 0; n < 2; ++n) _Pragma("unroll") for (int k = 0; k < 2; ++k) \
;         acc[ai][bj][m][n] = __builtin_amdgcn_mfma_f32_16x16x32_bf16(Bt[n][k], At[m][k], acc[ai][bj][m][n], 0, 0, 0); __builtin_amdgcn_s_setprio(0); } while (0)
; #define PG8_WAIT_V(n) asm volatile("s_waitcnt vmcnt(" #n ")" ::: "memory")
; #define PG8_WAIT_L(n) asm volatile("s_waitcnt lgkmcnt(" #n ")" ::: "memory")
; #define PG8_BAR __builtin_amdgcn_s_barrier()
; #define PG8_SCHED __builtin_amdgcn_sched_barrier(0)
; template <class Epi>
; __device__ __forceinline__ void gemm_phase(LAS unsigned char* lds, const Gemm g, const StaticOrder& S, const Epi& E) {
;     ...
;             PG8_LDB(B0, 0, 0); PG8_SCHED; PG8_LDA(At, 0, 0); PG8_STAGE(PG8_SA(1, 1), a1 + hstep, voffA);
;             PG8_WAIT_L(8); PG8_BAR; PG8_WAIT_L(0); PG8_MMA(0, 0, At, B0); PG8_BAR; PG8_SCHED;
;             PG8_LDB(B1, 0, 1); PG8_STAGE(PG8_SB(0, 0), b2, voffB);
;             PG8_BAR; PG8_WAIT_L(0); PG8_MMA(0, 1, At, B1); PG8_BAR;
;             PG8_LDA(At, 0, 1); PG8_STAGE(PG8_SA(0, 0), a2, voffA);
;             PG8_BAR; PG8_WAIT_L(0); PG8_MMA(1, 0, At, B0); PG8_BAR; PG8_SCHED;
;             PG8_STAGE(PG8_SB(0, 1), b2 + hstep, voffB);
;             PG8_WAIT_V(6); PG8_BAR; PG8_MMA(1, 1, At, B1); PG8_BAR;
.LBB0_559:
	ds_read_b128 v[156:159], v133
	ds_read_b128 v[160:163], v133 offset:1024
	ds_read_b128 v[164:167], v133 offset:2048
	ds_read_b128 v[168:171], v133 offset:3072
	s_add_u32 s34, s30, 0xfff80080
	s_addc_u32 s35, s31, -1
	s_cmp_eq_u32 s65, 28
	s_cselect_b32 s41, s25, s35
	s_cselect_b32 s40, s61, s34
	s_cselect_b32 s35, s23, s64
	s_cselect_b32 s34, s62, s63
	s_add_i32 m0, s21, 0xc000
	ds_read_b128 v[172:175], v153
	ds_read_b128 v[176:179], v153 offset:1024
	ds_read_b128 v[180:183], v153 offset:2048
	ds_read_b128 v[184:187], v153 offset:3072
	ds_read_b128 v[188:191], v153 offset:4096
	ds_read_b128 v[192:195], v153 offset:5120
	ds_read_b128 v[196:199], v153 offset:6144
	ds_read_b128 v[200:203], v153 offset:7168
	global_load_lds_dwordx4 v142, s[30:31]
	s_add_i32 m0, s21, 0xe000
	s_nop 0
	global_load_lds_dwordx4 v144, s[30:31]
	s_waitcnt lgkmcnt(8)
	s_barrier
	s_waitcnt lgkmcnt(0)
	s_waitcnt lgkmcnt(0)
	v_mfma_f32_16x16x32_bf16 v[124:127], v[156:159], v[172:175], v[124:127]
	v_mfma_f32_16x16x32_bf16 v[120:123], v[164:167], v[172:175], v[120:123]
	v_mfma_f32_16x16x32_bf16 v[116:119], v[156:159], v[180:183], v[116:119]
	v_mfma_f32_16x16x32_bf16 v[112:115], v[164:167], v[180:183], v[112:115]
	v_mfma_f32_16x16x32_bf16 v[100:103], v[156:159], v[188:191], v[100:103]
	v_mfma_f32_16x16x32_bf16 v[96:99], v[164:167], v[188:191], v[96:99]
	v_mfma_f32_16x16x32_bf16 v[84:87], v[156:159], v[196:199], v[84:87]
	v_mfma_f32_16x16x32_bf16 v[80:83], v[164:167], v[196:199], v[80:83]
	v_mfma_f32_16x16x32_bf16 v[124:127], v[160:163], v[176:179], v[124:127]
	v_mfma_f32_16x16x32_bf16 v[120:123], v[168:171], v[176:179], v[120:123]
	v_mfma_f32_16x16x32_bf16 v[116:119], v[160:163], v[184:187], v[116:119]
	v_mfma_f32_16x16x32_bf16 v[112:115], v[168:171], v[184:187], v[112:115]
	v_mfma_f32_16x16x32_bf16 v[100:103], v[160:163], v[192:195], v[100:103]
	v_mfma_f32_16x16x32_bf16 v[96:99], v[168:171], v[192:195], v[96:99]
	v_mfma_f32_16x16x32_bf16 v[84:87], v[160:163], v[200:203], v[84:87]
	v_mfma_f32_16x16x32_bf16 v[80:83], v[168:171], v[200:203], v[80:83]
	s_barrier
	s_add_i32 s66, s54, s43
	s_add_u32 s72, s34, 0x80
	s_addc_u32 s73, s35, 0
	s_mov_b32 m0, s66
	ds_read_b128 v[204:207], v154
	ds_read_b128 v[208:211], v154 offset:1024
	ds_read_b128 v[212:215], v154 offset:2048
	ds_read_b128 v[216:219], v154 offset:3072
	global_load_lds_dwordx4 v138, s[34:35]
	s_add_i32 m0, s66, 0x2000
	s_nop 0
	global_load_lds_dwordx4 v134, s[34:35]
	s_barrier
	s_waitcnt lgkmcnt(0)
	s_waitcnt lgkmcnt(0)
	v_mfma_f32_16x16x32_bf16 v[108:111], v[204:207], v[172:175], v[108:111]
	v_mfma_f32_16x16x32_bf16 v[104:107], v[212:215], v[172:175], v[104:107]
	v_mfma_f32_16x16x32_bf16 v[92:95], v[204:207], v[180:183], v[92:95]
	v_mfma_f32_16x16x32_bf16 v[88:91], v[212:215], v[180:183], v[88:91]
	v_mfma_f32_16x16x32_bf16 v[76:79], v[204:207], v[188:191], v[76:79]
	v_mfma_f32_16x16x32_bf16 v[72:75], v[212:215], v[188:191], v[72:75]
	v_mfma_f32_16x16x32_bf16 v[68:71], v[204:207], v[196:199], v[68:71]
	v_mfma_f32_16x16x32_bf16 v[64:67], v[212:215], v[196:199], v[64:67]
	v_mfma_f32_16x16x32_bf16 v[108:111], v[208:211], v[176:179], v[108:111]
	v_mfma_f32_16x16x32_bf16 v[104:107], v[216:219], v[176:179], v[104:107]
	v_mfma_f32_16x16x32_bf16 v[92:95], v[208:211], v[184:187], v[92:95]
	v_mfma_f32_16x16x32_bf16 v[88:91], v[216:219], v[184:187], v[88:91]
	v_mfma_f32_16x16x32_bf16 v[76:79], v[208:211], v[192:195], v[76:79]
	v_mfma_f32_16x16x32_bf16 v[72:75], v[216:219], v[192:195], v[72:75]
	v_mfma_f32_16x16x32_bf16 v[68:71], v[208:211], v[200:203], v[68:71]
	v_mfma_f32_16x16x32_bf16 v[64:67], v[216:219], v[200:203], v[64:67]
	s_mov_b32 m0, s21
	s_add_u32 s74, s40, 0x80
	s_addc_u32 s75, s41, 0
	s_barrier
	ds_read_b128 v[172:175], v153 offset:16384
	ds_read_b128 v[176:179], v153 offset:17408
	ds_read_b128 v[180:183], v153 offset:18432
	ds_read_b128 v[184:187], v153 offset:19456
	ds_read_b128 v[188:191], v153 offset:20480
	ds_read_b128 v[192:195], v153 offset:21504
	ds_read_b128 v[196:199], v153 offset:22528
	ds_read_b128 v[200:203], v153 offset:23552
	global_load_lds_dwordx4 v140, s[40:41]
	s_mov_b32 m0, s46
	s_nop 0
	global_load_lds_dwordx4 v136, s[40:41]
	s_barrier
	s_waitcnt lgkmcnt(0)
	s_waitcnt lgkmcnt(0)
	v_mfma_f32_16x16x32_bf16 v[60:63], v[156:159], v[172:175], v[60:63]
	v_mfma_f32_16x16x32_bf16 v[56:59], v[164:167], v[172:175], v[56:59]
	v_mfma_f32_16x16x32_bf16 v[52:55], v[156:159], v[180:183], v[52:55]
	v_mfma_f32_16x16x32_bf16 v[48:51], v[164:167], v[180:183], v[48:51]
	v_mfma_f32_16x16x32_bf16 v[36:39], v[156:159], v[188:191], v[36:39]
	v_mfma_f32_16x16x32_bf16 v[32:35], v[164:167], v[188:191], v[32:35]
	v_mfma_f32_16x16x32_bf16 v[20:23], v[156:159], v[196:199], v[20:23]
	v_mfma_f32_16x16x32_bf16 v[16:19], v[164:167], v[196:199], v[16:19]
	v_mfma_f32_16x16x32_bf16 v[60:63], v[160:163], v[176:179], v[60:63]
	v_mfma_f32_16x16x32_bf16 v[56:59], v[168:171], v[176:179], v[56:59]
	v_mfma_f32_16x16x32_bf16 v[52:55], v[160:163], v[184:187], v[52:55]
	v_mfma_f32_16x16x32_bf16 v[48:51], v[168:171], v[184:187], v[48:51]
	v_mfma_f32_16x16x32_bf16 v[36:39], v[160:163], v[192:195], v[36:39]
	v_mfma_f32_16x16x32_bf16 v[32:35], v[168:171], v[192:195], v[32:35]
	v_mfma_f32_16x16x32_bf16 v[20:23], v[160:163], v[200:203], v[20:23]
	v_mfma_f32_16x16x32_bf16 v[16:19], v[168:171], v[200:203], v[16:19]
	s_barrier
	s_add_u32 s66, s34, 0x80000
	s_addc_u32 s67, s35, 0
	s_add_i32 s68, s55, s43
	s_mov_b32 m0, s68
	s_nop 0
	global_load_lds_dwordx4 v138, s[66:67]
	s_add_i32 m0, s68, 0x2000
	s_nop 0
	global_load_lds_dwordx4 v134, s[66:67]
	s_waitcnt vmcnt(6)
	s_barrier
; #define PG8_STAGE(bufoff, gbase, voff) do { _Pragma("unroll") for (int _i = 0; _i < 2; ++_i) \
;         __builtin_amdgcn_global_load_lds((const unsigned*)((const char*)(gbase) + (voff)[_i]), (LAS unsigned*)(lds + (bufoff) + ldsw + _i * 8192), 16, 0, 0); } while (0)
; #define PG8_LDA(dst, b, h) do { _Pragma("unroll") for (int m = 0; m < 4; ++m) _Pragma("unroll") for (int k = 0; k < 2; ++k) dst[m][k] = *(const LAS bf16x8*)(lds + PG8_SA(b, h) + aoff + m * 2048 + k * 1024); } while (0)
; #define PG8_LDB(dst, b, h) do { _Pragma("unroll") for (int n = 0; n < 2; ++n) _Pragma("unroll") for (int k = 0; k < 2; ++k) dst[n][k] = *(const LAS bf16x8*)(lds + PG8_SB(b, h) + boff + n * 2048 + k * 1024); } while (0)
; #define PG8_MMA(ai, bj, At, Bt) do { __builtin_amdgcn_s_setprio(1); _Pragma("unroll") for (int m = 0; m < 4; ++m) _Pragma("unroll") for (int n = 0; n < 2; ++n) _Pragma("unroll") for (int k = 0; k < 2; ++k) \
;         acc[ai][bj][m][n] = __builtin_amdgcn_mfma_f32_16x16x32_bf16(Bt[n][k], At[m][k], acc[ai][bj][m][n], 0, 0, 0); __builtin_amdgcn_s_setprio(0); } while (0)
; #define PG8_WAIT_V(n) asm volatile("s_waitcnt vmcnt(" #n ")" ::: "memory")
; #define PG8_WAIT_L(n) asm volatile("s_waitcnt lgkmcnt(" #n ")" ::: "memory")
; #define PG8_BAR __builtin_amdgcn_s_barrier()
; #define PG8_SCHED __builtin_amdgcn_sched_barrier(0)
; template <class Epi>
; __device__ __forceinline__ void gemm_phase(LAS unsigned char* lds, const Gemm g, const StaticOrder& S, const Epi& E) {
;     ...
;             PG8_WAIT_V(6); PG8_BAR; PG8_MMA(1, 1, At, B1); PG8_BAR;
;             PG8_LDB(B0, 1, 0); PG8_SCHED; PG8_LDA(At, 1, 0); PG8_STAGE(PG8_SA(0, 1), a2 + hstep, voffA);
;             PG8_WAIT_L(8); PG8_BAR; PG8_WAIT_L(0); PG8_MMA(0, 0, At, B0); PG8_BAR; PG8_SCHED;
;             PG8_LDB(B1, 1, 1); PG8_STAGE(PG8_SB(1, 0), b3, voffB);
;             PG8_BAR; PG8_WAIT_L(0); PG8_MMA(0, 1, At, B1); PG8_BAR;
;             PG8_LDA(At, 1, 1); PG8_STAGE(PG8_SA(1, 0), a3, voffA);
	v_mfma_f32_16x16x32_bf16 v[44:47], v[204:207], v[172:175], v[44:47]
	v_mfma_f32_16x16x32_bf16 v[40:43], v[212:215], v[172:175], v[40:43]
	v_mfma_f32_16x16x32_bf16 v[28:31], v[204:207], v[180:183], v[28:31]
	v_mfma_f32_16x16x32_bf16 v[24:27], v[212:215], v[180:183], v[24:27]
	v_mfma_f32_16x16x32_bf16 v[12:15], v[204:207], v[188:191], v[12:15]
	v_mfma_f32_16x16x32_bf16 v[8:11], v[212:215], v[188:191], v[8:11]
	v_mfma_f32_16x16x32_bf16 v[4:7], v[204:207], v[196:199], v[4:7]
	v_mfma_f32_16x16x32_bf16 v[0:3], v[212:215], v[196:199], v[0:3]
	v_mfma_f32_16x16x32_bf16 v[44:47], v[208:211], v[176:179], v[44:47]
	v_mfma_f32_16x16x32_bf16 v[40:43], v[216:219], v[176:179], v[40:43]
	v_mfma_f32_16x16x32_bf16 v[28:31], v[208:211], v[184:187], v[28:31]
	v_mfma_f32_16x16x32_bf16 v[24:27], v[216:219], v[184:187], v[24:27]
	v_mfma_f32_16x16x32_bf16 v[12:15], v[208:211], v[192:195], v[12:15]
	v_mfma_f32_16x16x32_bf16 v[8:11], v[216:219], v[192:195], v[8:11]
	v_mfma_f32_16x16x32_bf16 v[4:7], v[208:211], v[200:203], v[4:7]
	v_mfma_f32_16x16x32_bf16 v[0:3], v[216:219], v[200:203], v[0:3]
	s_add_i32 s66, 0, 0x18000
	v_add_u32_e32 v155, s66, v151
	s_barrier
	ds_read_b128 v[156:159], v155
	ds_read_b128 v[160:163], v155 offset:1024
	ds_read_b128 v[164:167], v155 offset:2048
	ds_read_b128 v[168:171], v155 offset:3072
	s_add_u32 s40, s40, 0x80000
	s_addc_u32 s41, s41, 0
	s_mov_b32 m0, s47
	ds_read_b128 v[172:175], v153 offset:32768
	ds_read_b128 v[176:179], v153 offset:33792
	ds_read_b128 v[180:183], v153 offset:34816
	ds_read_b128 v[184:187], v153 offset:35840
	ds_read_b128 v[188:191], v153 offset:36864
	ds_read_b128 v[192:195], v153 offset:37888
	ds_read_b128 v[196:199], v153 offset:38912
	ds_read_b128 v[200:203], v153 offset:39936
	global_load_lds_dwordx4 v140, s[40:41]
	s_mov_b32 m0, s48
	s_nop 0
	global_load_lds_dwordx4 v136, s[40:41]
	s_waitcnt lgkmcnt(8)
	s_barrier
	s_waitcnt lgkmcnt(0)
	s_waitcnt lgkmcnt(0)
	v_mfma_f32_16x16x32_bf16 v[124:127], v[156:159], v[172:175], v[124:127]
	v_mfma_f32_16x16x32_bf16 v[120:123], v[164:167], v[172:175], v[120:123]
	v_mfma_f32_16x16x32_bf16 v[116:119], v[156:159], v[180:183], v[116:119]
	v_mfma_f32_16x16x32_bf16 v[112:115], v[164:167], v[180:183], v[112:115]
	v_mfma_f32_16x16x32_bf16 v[100:103], v[156:159], v[188:191], v[100:103]
	v_mfma_f32_16x16x32_bf16 v[96:99], v[164:167], v[188:191], v[96:99]
	v_mfma_f32_16x16x32_bf16 v[84:87], v[156:159], v[196:199], v[84:87]
	v_mfma_f32_16x16x32_bf16 v[80:83], v[164:167], v[196:199], v[80:83]
	v_mfma_f32_16x16x32_bf16 v[124:127], v[160:163], v[176:179], v[124:127]
	v_mfma_f32_16x16x32_bf16 v[120:123], v[168:171], v[176:179], v[120:123]
	v_mfma_f32_16x16x32_bf16 v[116:119], v[160:163], v[184:187], v[116:119]
	v_mfma_f32_16x16x32_bf16 v[112:115], v[168:171], v[184:187], v[112:115]
	v_mfma_f32_16x16x32_bf16 v[100:103], v[160:163], v[192:195], v[100:103]
	v_mfma_f32_16x16x32_bf16 v[96:99], v[168:171], v[192:195], v[96:99]
	v_mfma_f32_16x16x32_bf16 v[84:87], v[160:163], v[200:203], v[84:87]
	v_mfma_f32_16x16x32_bf16 v[80:83], v[168:171], v[200:203], v[80:83]
	s_barrier
	s_add_i32 s40, 0, 0x1c000
	s_add_i32 s41, s66, s43
	v_add_u32_e32 v155, s40, v151
	s_mov_b32 m0, s41
	ds_read_b128 v[204:207], v155
	ds_read_b128 v[208:211], v155 offset:1024
	ds_read_b128 v[212:215], v155 offset:2048
	ds_read_b128 v[216:219], v155 offset:3072
	global_load_lds_dwordx4 v138, s[72:73]
	s_add_i32 m0, s41, 0x2000
	s_nop 0
	global_load_lds_dwordx4 v134, s[72:73]
	s_barrier
	s_waitcnt lgkmcnt(0)
	s_waitcnt lgkmcnt(0)
	v_mfma_f32_16x16x32_bf16 v[108:111], v[204:207], v[172:175], v[108:111]
	v_mfma_f32_16x16x32_bf16 v[104:107], v[212:215], v[172:175], v[104:107]
	v_mfma_f32_16x16x32_bf16 v[92:95], v[204:207], v[180:183], v[92:95]
	v_mfma_f32_16x16x32_bf16 v[88:91], v[212:215], v[180:183], v[88:91]
	v_mfma_f32_16x16x32_bf16 v[76:79], v[204:207], v[188:191], v[76:79]
	v_mfma_f32_16x16x32_bf16 v[72:75], v[212:215], v[188:191], v[72:75]
	v_mfma_f32_16x16x32_bf16 v[68:71], v[204:207], v[196:199], v[68:71]
	v_mfma_f32_16x16x32_bf16 v[64:67], v[212:215], v[196:199], v[64:67]
	v_mfma_f32_16x16x32_bf16 v[108:111], v[208:211], v[176:179], v[108:111]
	v_mfma_f32_16x16x32_bf16 v[104:107], v[216:219], v[176:179], v[104:107]
	v_mfma_f32_16x16x32_bf16 v[92:95], v[208:211], v[184:187], v[92:95]
	v_mfma_f32_16x16x32_bf16 v[88:91], v[216:219], v[184:187], v[88:91]
	v_mfma_f32_16x16x32_bf16 v[76:79], v[208:211], v[192:195], v[76:79]
	v_mfma_f32_16x16x32_bf16 v[72:75], v[216:219], v[192:195], v[72:75]
	v_mfma_f32_16x16x32_bf16 v[68:71], v[208:211], v[200:203], v[68:71]
	v_mfma_f32_16x16x32_bf16 v[64:67], v[216:219], v[200:203], v[64:67]
	s_mov_b32 m0, s50
	s_barrier
	ds_read_b128 v[172:175], v153 offset:49152
	ds_read_b128 v[176:179], v153 offset:50176
	ds_read_b128 v[180:183], v153 offset:51200
	ds_read_b128 v[184:187], v153 offset:52224
	ds_read_b128 v[188:191], v153 offset:53248
	ds_read_b128 v[192:195], v153 offset:54272
	ds_read_b128 v[196:199], v153 offset:55296
	ds_read_b128 v[200:203], v153 offset:56320
	global_load_lds_dwordx4 v140, s[74:75]
	s_mov_b32 m0, s51
	s_nop 0
	global_load_lds_dwordx4 v136, s[74:75]
	s_barrier
; #define PG8_STAGE(bufoff, gbase, voff) do { _Pragma("unroll") for (int _i = 0; _i < 2; ++_i) \
;         __builtin_amdgcn_global_load_lds((const unsigned*)((const char*)(gbase) + (voff)[_i]), (LAS unsigned*)(lds + (bufoff) + ldsw + _i * 8192), 16, 0, 0); } while (0)
; #define PG8_LDA(dst, b, h) do { _Pragma("unroll") for (int m = 0; m < 4; ++m) _Pragma("unroll") for (int k = 0; k < 2; ++k) dst[m][k] = *(const LAS bf16x8*)(lds + PG8_SA(b, h) + aoff + m * 2048 + k * 1024); } while (0)
; #define PG8_MMA(ai, bj, At, Bt) do { __builtin_amdgcn_s_setprio(1); _Pragma("unroll") for (int m = 0; m < 4; ++m) _Pragma("unroll") for (int n = 0; n < 2; ++n) _Pragma("unroll") for (int k = 0; k < 2; ++k) \
;         acc[ai][bj][m][n] = __builtin_amdgcn_mfma_f32_16x16x32_bf16(Bt[n][k], At[m][k], acc[ai][bj][m][n], 0, 0, 0); __builtin_amdgcn_s_setprio(0); } while (0)
; #define PG8_WAIT_V(n) asm volatile("s_waitcnt vmcnt(" #n ")" ::: "memory")
; #define PG8_WAIT_L(n) asm volatile("s_waitcnt lgkmcnt(" #n ")" ::: "memory")
; #define PG8_BAR __builtin_amdgcn_s_barrier()
; #define PG8_SCHED __builtin_amdgcn_sched_barrier(0)
; template <class Epi>
; __device__ __forceinline__ void gemm_phase(LAS unsigned char* lds, const Gemm g, const StaticOrder& S, const Epi& E) {
;     ...
;             PG8_BAR; PG8_WAIT_L(0); PG8_MMA(0, 1, At, B1); PG8_BAR;
;             PG8_LDA(At, 1, 1); PG8_STAGE(PG8_SA(1, 0), a3, voffA);
;             PG8_BAR; PG8_WAIT_L(0); PG8_MMA(1, 0, At, B0); PG8_BAR; PG8_SCHED;
;             PG8_STAGE(PG8_SB(1, 1), b3 + hstep, voffB);
;             PG8_WAIT_V(6); PG8_BAR; PG8_MMA(1, 1, At, B1); PG8_BAR;
	s_waitcnt lgkmcnt(0)
	s_waitcnt lgkmcnt(0)
	v_mfma_f32_16x16x32_bf16 v[60:63], v[156:159], v[172:175], v[60:63]
	v_mfma_f32_16x16x32_bf16 v[56:59], v[164:167], v[172:175], v[56:59]
	v_mfma_f32_16x16x32_bf16 v[52:55], v[156:159], v[180:183], v[52:55]
	v_mfma_f32_16x16x32_bf16 v[48:51], v[164:167], v[180:183], v[48:51]
	v_mfma_f32_16x16x32_bf16 v[36:39], v[156:159], v[188:191], v[36:39]
	v_mfma_f32_16x16x32_bf16 v[32:35], v[164:167], v[188:191], v[32:35]
	v_mfma_f32_16x16x32_bf16 v[20:23], v[156:159], v[196:199], v[20:23]
	v_mfma_f32_16x16x32_bf16 v[16:19], v[164:167], v[196:199], v[16:19]
	v_mfma_f32_16x16x32_bf16 v[60:63], v[160:163], v[176:179], v[60:63]
	v_mfma_f32_16x16x32_bf16 v[56:59], v[168:171], v[176:179], v[56:59]
	v_mfma_f32_16x16x32_bf16 v[52:55], v[160:163], v[184:187], v[52:55]
	v_mfma_f32_16x16x32_bf16 v[48:51], v[168:171], v[184:187], v[48:51]
	v_mfma_f32_16x16x32_bf16 v[36:39], v[160:163], v[192:195], v[36:39]
	v_mfma_f32_16x16x32_bf16 v[32:35], v[168:171], v[192:195], v[32:35]
	v_mfma_f32_16x16x32_bf16 v[20:23], v[160:163], v[200:203], v[20:23]
	v_mfma_f32_16x16x32_bf16 v[16:19], v[168:171], v[200:203], v[16:19]
	s_barrier
	s_add_u32 s34, s34, 0x80080
	s_addc_u32 s35, s35, 0
	s_add_i32 s40, s40, s43
	s_mov_b32 m0, s40
	s_nop 0
	global_load_lds_dwordx4 v138, s[34:35]
	s_add_i32 m0, s40, 0x2000
	s_nop 0
	global_load_lds_dwordx4 v134, s[34:35]
	s_waitcnt vmcnt(6)
	s_barrier
	v_mfma_f32_16x16x32_bf16 v[44:47], v[204:207], v[172:175], v[44:47]
	v_mfma_f32_16x16x32_bf16 v[40:43], v[212:215], v[172:175], v[40:43]
	v_mfma_f32_16x16x32_bf16 v[28:31], v[204:207], v[180:183], v[28:31]
	v_mfma_f32_16x16x32_bf16 v[24:27], v[212:215], v[180:183], v[24:27]
	v_mfma_f32_16x16x32_bf16 v[12:15], v[204:207], v[188:191], v[12:15]
	v_mfma_f32_16x16x32_bf16 v[8:11], v[212:215], v[188:191], v[8:11]
	v_mfma_f32_16x16x32_bf16 v[4:7], v[204:207], v[196:199], v[4:7]
	v_mfma_f32_16x16x32_bf16 v[0:3], v[212:215], v[196:199], v[0:3]
	v_mfma_f32_16x16x32_bf16 v[44:47], v[208:211], v[176:179], v[44:47]
	v_mfma_f32_16x16x32_bf16 v[40:43], v[216:219], v[176:179], v[40:43]
	v_mfma_f32_16x16x32_bf16 v[28:31], v[208:211], v[184:187], v[28:31]
	v_mfma_f32_16x16x32_bf16 v[24:27], v[216:219], v[184:187], v[24:27]
	v_mfma_f32_16x16x32_bf16 v[12:15], v[208:211], v[192:195], v[12:15]
	v_mfma_f32_16x16x32_bf16 v[8:11], v[216:219], v[192:195], v[8:11]
	v_mfma_f32_16x16x32_bf16 v[4:7], v[208:211], v[200:203], v[4:7]
	v_mfma_f32_16x16x32_bf16 v[0:3], v[216:219], v[200:203], v[0:3]
	s_add_i32 s65, s65, 2
	s_add_u32 s30, s30, 0x100
	s_addc_u32 s31, s31, 0
	s_add_u32 s63, s63, 0x100
	s_addc_u32 s64, s64, 0
	s_cmp_gt_u32 s65, 29
	s_barrier
	s_cbranch_scc0 .LBB0_559
; __device__ __forceinline__ unsigned pk_bf16(float lo, float hi) { const f32x2 v = (f32x2){lo, hi}; const bf16v2 b = __builtin_convertvector(v, bf16v2); return __builtin_bit_cast(unsigned, b); }
; #define PG8_WAIT_V(n) asm volatile("s_waitcnt vmcnt(" #n ")" ::: "memory")
; #define PG8_BAR __builtin_amdgcn_s_barrier()
; template <class Epi>
; __device__ __forceinline__ void gemm_phase(LAS unsigned char* lds, const Gemm g, const StaticOrder& S, const Epi& E) {
;     ...
;         if (!has_next) break;
; #pragma unroll
;         for (int a = 0; a < 2; ++a)
; #pragma unroll
;             for (int b = 0; b < 2; ++b)
; #pragma unroll
;                 for (int m = 0; m < 4; ++m)
; #pragma unroll
;                     for (int n = 0; n < 2; ++n) acc[a][b][m][n] = (f32x4){0.f, 0.f, 0.f, 0.f};
;         cur = nxt; cA = nA; cB = nB; ++ui;
;     }
;     PG8_WAIT_V(0);
;     if (wr == 0) PG8_BAR;
;     __device__ __forceinline__ void operator()(const f32x4 (&acc)[2][2][4][2], const pg8::Unit& u, int wr, int wc, int fr, int fq) const {
;         const int row0 = u.pm * 256 + wr * 64 + fr, col0 = u.pn * 256 + wc * 32 + 8 * fq;
; #pragma unroll
;         for (int ai = 0; ai < 2; ++ai)
; #pragma unroll
;             for (int m = 0; m < 4; ++m) {
;                 const int row = row0 + ai * 128 + m * 16;
;                 bf16_t* orow = yb + (size_t)row * DM + col0;
; #pragma unroll
;                 for (int bj = 0; bj < 2; ++bj) {
;                     const f32x4 v0 = acc[ai][bj][m][0], v1 = acc[ai][bj][m][1];
;                     *(u32x4*)(orow + bj * 128) = (u32x4){pk_bf16(v0[0], v0[1]), pk_bf16(v0[2], v0[3]), pk_bf16(v1[0], v1[1]), pk_bf16(v1[2], v1[3])};
;                 }
;             }
	v_lshl_add_u32 v156, s20, 8, v150
	v_lshl_or_b32 v158, s60, 8, v152
	v_ashrrev_i32_e32 v157, 31, v156
	v_ashrrev_i32_e32 v159, 31, v158
	v_lshlrev_b64 v[160:161], 12, v[156:157]
	v_lshl_add_u64 v[160:161], s[6:7], 0, v[160:161]
	v_lshlrev_b64 v[158:159], 1, v[158:159]
	v_lshl_add_u64 v[160:161], v[160:161], 0, v[158:159]
	v_cvt_pk_bf16_f32 v60, v60, v61
	v_cvt_pk_bf16_f32 v61, v62, v63
	v_cvt_pk_bf16_f32 v62, v56, v57
	v_add_co_u32_e32 v56, vcc, s56, v160
	v_cvt_pk_bf16_f32 v68, v68, v69
	v_cvt_pk_bf16_f32 v69, v70, v71
	v_cvt_pk_bf16_f32 v70, v64, v65
	v_lshl_add_u64 v[64:65], v[160:161], 0, s[10:11]
	v_addc_co_u32_e32 v57, vcc, 0, v161, vcc
	v_cvt_pk_bf16_f32 v44, v44, v45
	v_cvt_pk_bf16_f32 v45, v46, v47
	v_cvt_pk_bf16_f32 v46, v40, v41
	v_cvt_pk_bf16_f32 v47, v42, v43
	v_cvt_pk_bf16_f32 v108, v108, v109
	v_cvt_pk_bf16_f32 v109, v110, v111
	v_cvt_pk_bf16_f32 v110, v104, v105
	v_or_b32_e32 v104, 16, v156
	global_store_dwordx4 v[64:65], v[44:47], off offset:256
	v_ashrrev_i32_e32 v105, 31, v104
	v_cvt_pk_bf16_f32 v92, v92, v93
	v_add_co_u32_e32 v46, vcc, s57, v160
	v_cvt_pk_bf16_f32 v93, v94, v95
	v_cvt_pk_bf16_f32 v94, v88, v89
	v_or_b32_e32 v88, 32, v156
	v_lshl_add_u64 v[44:45], v[160:161], 0, s[14:15]
	v_addc_co_u32_e32 v47, vcc, 0, v161, vcc
	v_cvt_pk_bf16_f32 v28, v28, v29
	v_cvt_pk_bf16_f32 v29, v30, v31
	v_cvt_pk_bf16_f32 v30, v24, v25
	v_cvt_pk_bf16_f32 v31, v26, v27
	v_lshlrev_b64 v[104:105], 12, v[104:105]
	v_ashrrev_i32_e32 v89, 31, v88
	v_cvt_pk_bf16_f32 v76, v76, v77
	v_cvt_pk_bf16_f32 v77, v78, v79
	v_cvt_pk_bf16_f32 v78, v72, v73
	v_or_b32_e32 v72, 48, v156
	global_store_dwordx4 v[44:45], v[28:31], off offset:256
	v_cvt_pk_bf16_f32 v111, v106, v107
	v_lshl_add_u64 v[104:105], s[6:7], 0, v[104:105]
	v_add_co_u32_e32 v30, vcc, s58, v160
	v_lshlrev_b64 v[88:89], 12, v[88:89]
	v_ashrrev_i32_e32 v73, 31, v72
	v_lshl_add_u64 v[28:29], v[160:161], 0, s[16:17]
	v_addc_co_u32_e32 v31, vcc, 0, v161, vcc
	v_cvt_pk_bf16_f32 v12, v12, v13
	v_cvt_pk_bf16_f32 v13, v14, v15
	v_cvt_pk_bf16_f32 v14, v8, v9
	v_cvt_pk_bf16_f32 v15, v10, v11
	global_store_dwordx4 v[160:161], v[108:111], off offset:256
	v_cvt_pk_bf16_f32 v95, v90, v91
	v_lshl_add_u64 v[88:89], s[6:7], 0, v[88:89]
	v_lshl_add_u64 v[108:109], v[104:105], 0, v[158:159]
	v_lshlrev_b64 v[72:73], 12, v[72:73]
	global_store_dwordx4 v[28:29], v[12:15], off offset:256
	global_store_dwordx4 v[108:109], v[92:95], off offset:256
	v_cvt_pk_bf16_f32 v79, v74, v75
	v_add_co_u32_e32 v14, vcc, s59, v160
	v_lshl_add_u64 v[92:93], v[88:89], 0, v[158:159]
	v_lshl_add_u64 v[72:73], s[6:7], 0, v[72:73]
	v_addc_co_u32_e32 v15, vcc, 0, v161, vcc
	v_cvt_pk_bf16_f32 v124, v124, v125
	v_cvt_pk_bf16_f32 v125, v126, v127
	v_cvt_pk_bf16_f32 v126, v120, v121
	v_cvt_pk_bf16_f32 v127, v122, v123
	v_cvt_pk_bf16_f32 v104, v116, v117
	v_cvt_pk_bf16_f32 v105, v118, v119
	v_cvt_pk_bf16_f32 v106, v112, v113
	v_cvt_pk_bf16_f32 v107, v114, v115
	v_cvt_pk_bf16_f32 v88, v100, v101
	v_cvt_pk_bf16_f32 v89, v102, v103
	v_cvt_pk_bf16_f32 v90, v96, v97
	v_cvt_pk_bf16_f32 v91, v98, v99
	global_store_dwordx4 v[92:93], v[76:79], off offset:256
	v_cvt_pk_bf16_f32 v74, v80, v81
	v_cvt_pk_bf16_f32 v75, v82, v83
	v_lshl_add_u64 v[76:77], v[72:73], 0, v[158:159]
	v_cvt_pk_bf16_f32 v72, v84, v85
	v_cvt_pk_bf16_f32 v73, v86, v87
	v_cvt_pk_bf16_f32 v71, v66, v67
	v_cvt_pk_bf16_f32 v63, v58, v59
	v_cvt_pk_bf16_f32 v40, v52, v53
	v_cvt_pk_bf16_f32 v41, v54, v55
	v_cvt_pk_bf16_f32 v42, v48, v49
	v_cvt_pk_bf16_f32 v43, v50, v51
	v_cvt_pk_bf16_f32 v24, v36, v37
	v_cvt_pk_bf16_f32 v25, v38, v39
	v_cvt_pk_bf16_f32 v26, v32, v33
	v_cvt_pk_bf16_f32 v27, v34, v35
	v_lshl_add_u64 v[12:13], v[160:161], 0, s[18:19]
	v_cvt_pk_bf16_f32 v8, v20, v21
	v_cvt_pk_bf16_f32 v9, v22, v23
	v_cvt_pk_bf16_f32 v10, v16, v17
	v_cvt_pk_bf16_f32 v11, v18, v19
	v_cvt_pk_bf16_f32 v4, v4, v5
	v_cvt_pk_bf16_f32 v5, v6, v7
	v_cvt_pk_bf16_f32 v6, v0, v1
	v_cvt_pk_bf16_f32 v7, v2, v3
	s_and_b64 vcc, exec, s[8:9]
	s_mov_b32 s60, s22
	s_mov_b32 s20, s24
	s_mov_b64 s[34:35], s[28:29]
	s_mov_b64 s[30:31], s[26:27]
	s_mov_b32 s40, s70
	global_store_dwordx4 v[160:161], v[124:127], off
	global_store_dwordx4 v[108:109], v[104:107], off
	global_store_dwordx4 v[92:93], v[88:91], off
	global_store_dwordx4 v[76:77], v[72:75], off
	global_store_dwordx4 v[76:77], v[68:71], off offset:256
	global_store_dwordx4 v[56:57], v[60:63], off
	global_store_dwordx4 v[46:47], v[40:43], off
	global_store_dwordx4 v[30:31], v[24:27], off
	global_store_dwordx4 v[14:15], v[8:11], off
	global_store_dwordx4 v[12:13], v[4:7], off offset:256
	s_cbranch_vccnz .Lg2_exit
	s_cmp_lg_u32 s49, 4
	s_cbranch_scc1 .LBB0_556
	s_waitcnt vmcnt(0)
	s_barrier
	s_lshr_b32 s8, s42, 6
	s_cmp_lg_u32 s8, 4
	s_cbranch_scc1 .LBB0_556
	buffer_wbl2 sc1
	s_waitcnt vmcnt(0)
	s_mov_b64 s[8:9], exec
	s_mov_b64 exec, 1
	v_mov_b32_e32 v0, 0
	v_mov_b32_e32 v1, 1
	global_atomic_add v0, v1, s[36:37] offset:256
	s_mov_b64 exec, s[8:9]
	s_branch .LBB0_556
